# final norm_rows: gain loads hoisted (without the prep norm change)
# speedup vs baseline: 1.0451x; 1.0022x over previous
; __device__ __forceinline__ void norm_rows(CParams& p, int mode, const float* gain, int nrows) {
;     ...
;             for (int j = 0; j < 8; ++j) v[j] = *(const f32x4*)(H + (size_t)row * D + (lane + 64 * j) * 4);
;         }
;         float s = 0.f;
; #pragma unroll
;         for (int j = 0; j < 8; ++j) s += (v[j][0] * v[j][0] + v[j][1] * v[j][1]) + (v[j][2] * v[j][2] + v[j][3] * v[j][3]);
;         const float rs = 1.0f / sqrtf(wave_sum(s) * (1.0f / D) + EPS);
; #pragma unroll
;         for (int j = 0; j < 8; ++j) {
;             const f32x4 g = *(const f32x4*)(gain + (lane + 64 * j) * 4);
.LBB0_1463:
	v_lshl_add_u64 v[0:1], v[46:47], 0, v[32:33]
	global_load_dwordx4 v[28:31], v[0:1], off
	global_load_dwordx4 v[24:27], v[0:1], off offset:1024
	global_load_dwordx4 v[20:23], v[0:1], off offset:2048
	global_load_dwordx4 v[16:19], v[0:1], off offset:3072
	v_add_co_u32_e32 v70, vcc, 0x1000, v0
	s_nop 0
	v_addc_co_u32_e32 v71, vcc, 0, v1, vcc
	global_load_dwordx4 v[12:15], v[70:71], off
	global_load_dwordx4 v[8:11], v[70:71], off offset:1024
	global_load_dwordx4 v[4:7], v[70:71], off offset:2048
	global_load_dwordx4 v[0:3], v[70:71], off offset:3072
	global_load_dwordx4 v[120:123], v[36:37], off
	global_load_dwordx4 v[124:127], v[36:37], off offset:1024
	global_load_dwordx4 v[128:131], v[36:37], off offset:2048
	global_load_dwordx4 v[132:135], v[36:37], off offset:3072
	global_load_dwordx4 v[136:139], v[38:39], off
	global_load_dwordx4 v[140:143], v[40:41], off
	global_load_dwordx4 v[144:147], v[42:43], off
	global_load_dwordx4 v[148:151], v[44:45], off
	s_waitcnt vmcnt(0)
	v_add_u32_e32 v34, s50, v34
	v_lshl_add_u64 v[70:71], v[48:49], 0, v[32:33]
	v_lshl_add_u64 v[46:47], v[46:47], 0, s[20:21]
	v_lshl_add_u64 v[48:49], v[48:49], 0, s[20:21]
	v_mov_b32_e32 v74, v29
	v_mov_b32_e32 v75, v25
	v_mov_b32_e32 v78, v31
	v_mov_b32_e32 v79, v27
	v_mov_b32_e32 v72, v28
	v_mov_b32_e32 v73, v24
	v_mov_b32_e32 v76, v30
	v_mov_b32_e32 v77, v26
	v_pk_mul_f32 v[80:81], v[22:23], v[22:23]
	v_pk_mul_f32 v[82:83], v[20:21], v[20:21]
	v_pk_mul_f32 v[74:75], v[74:75], v[74:75]
	v_pk_mul_f32 v[78:79], v[78:79], v[78:79]
	v_pk_mov_b32 v[88:89], v[82:83], v[80:81] op_sel:[1,0]
	v_mov_b32_e32 v83, v81
	v_pk_fma_f32 v[72:73], v[72:73], v[72:73], v[74:75]
	v_pk_fma_f32 v[74:75], v[76:77], v[76:77], v[78:79]
	v_mul_f32_e32 v84, v17, v17
	v_mul_f32_e32 v86, v19, v19
	v_pk_add_f32 v[76:77], v[88:89], v[82:83]
	v_pk_add_f32 v[72:73], v[72:73], v[74:75]
	v_pk_fma_f32 v[80:81], v[16:17], v[16:17], v[84:85] op_sel_hi:[1,1,0]
	v_pk_fma_f32 v[84:85], v[18:19], v[18:19], v[86:87] op_sel_hi:[1,1,0]
	v_mul_f32_e32 v35, v12, v12
	v_mul_f32_e32 v65, v13, v13
	v_pk_add_f32 v[74:75], v[76:77], v[76:77] op_sel:[0,1] op_sel_hi:[1,0]
	v_pk_add_f32 v[72:73], v[72:73], v[72:73] op_sel:[0,1] op_sel_hi:[1,0]
	v_mul_f32_e32 v81, v14, v14
	v_mul_f32_e32 v85, v15, v15
	v_pk_mul_f32 v[78:79], v[10:11], v[10:11]
	v_pk_mul_f32 v[82:83], v[8:9], v[8:9]
	v_mov_b32_e32 v75, v65
	v_mov_b32_e32 v73, v35
	v_pk_mov_b32 v[76:77], v[82:83], v[78:79] op_sel:[1,0]
	v_mov_b32_e32 v83, v79
	v_pk_add_f32 v[80:81], v[80:81], v[84:85]
	v_pk_add_f32 v[72:73], v[72:73], v[74:75]
	v_mul_f32_e32 v89, v0, v0
	v_mul_f32_e32 v86, v5, v5
	v_mul_f32_e32 v88, v7, v7
	v_pk_add_f32 v[76:77], v[76:77], v[82:83]
	v_pk_add_f32 v[72:73], v[72:73], v[80:81]
	v_mul_f32_e32 v90, v1, v1
	v_mul_f32_e32 v91, v2, v2
	v_mul_f32_e32 v92, v3, v3
	v_pk_fma_f32 v[78:79], v[4:5], v[4:5], v[86:87] op_sel_hi:[1,1,0]
	v_pk_fma_f32 v[86:87], v[6:7], v[6:7], v[88:89] op_sel_hi:[1,1,0]
	v_pk_add_f32 v[76:77], v[76:77], v[76:77] op_sel:[0,1] op_sel_hi:[1,0]
	v_pk_add_f32 v[72:73], v[72:73], v[72:73] op_sel:[0,1] op_sel_hi:[1,0]
	v_mov_b32_e32 v79, v91
	v_mov_b32_e32 v87, v92
	v_mov_b32_e32 v77, v90
	v_mov_b32_e32 v73, v89
	v_pk_add_f32 v[78:79], v[78:79], v[86:87]
	v_pk_add_f32 v[72:73], v[72:73], v[76:77]
	s_nop 0
	v_pk_add_f32 v[72:73], v[72:73], v[78:79]
	s_nop 0
	v_add_f32_e32 v35, v72, v73
	ds_bpermute_b32 v65, v59, v35
	s_waitcnt lgkmcnt(0)
	v_add_f32_e32 v35, v35, v65
	ds_bpermute_b32 v65, v60, v35
	s_waitcnt lgkmcnt(0)
	v_add_f32_e32 v35, v35, v65
	ds_bpermute_b32 v65, v61, v35
	s_waitcnt lgkmcnt(0)
	v_add_f32_e32 v35, v35, v65
	ds_bpermute_b32 v65, v62, v35
	s_waitcnt lgkmcnt(0)
	v_add_f32_e32 v35, v35, v65
	ds_bpermute_b32 v65, v63, v35
	s_waitcnt lgkmcnt(0)
	v_add_f32_e32 v35, v35, v65
	ds_bpermute_b32 v65, v64, v35
	s_waitcnt lgkmcnt(0)
; __device__ __forceinline__ unsigned pk2(float lo, float hi) { const f32x2 v = {lo, hi}; const bf16v2 b = __builtin_convertvector(v, bf16v2); return __builtin_bit_cast(unsigned, b); }
; #define p (*kparams())
; __device__ __forceinline__ void norm_rows(CParams& p, int mode, const float* gain, int nrows) {
;     ...
;         const float rs = 1.0f / sqrtf(wave_sum(s) * (1.0f / D) + EPS);
; #pragma unroll
;         for (int j = 0; j < 8; ++j) {
;             const f32x4 g = *(const f32x4*)(gain + (lane + 64 * j) * 4);
;             const f32x4 y = v[j] * rs * g;
;             if (mode == 3) *(f32x4*)(p.out + (size_t)row * D + (lane + 64 * j) * 4) = y;
;             else { u32x2 w; w.x = pk2(y[0], y[1]); w.y = pk2(y[2], y[3]); *(u32x2*)(NB + (size_t)row * D + (lane + 64 * j) * 4) = w; }
;         }
	v_add_f32_e32 v35, v35, v65
	v_fmamk_f32 v35, v35, 0x3a000000, v50
	v_mul_f32_e32 v65, 0x4f800000, v35
	v_cmp_gt_f32_e32 vcc, s16, v35
	s_nop 1
	v_cndmask_b32_e32 v35, v35, v65, vcc
	v_sqrt_f32_e32 v65, v35
	s_nop 0
	v_add_u32_e32 v72, -1, v65
	v_add_u32_e32 v73, 1, v65
	v_fma_f32 v74, -v72, v65, v35
	v_fma_f32 v75, -v73, v65, v35
	v_cmp_ge_f32_e64 s[2:3], 0, v74
	s_nop 1
	v_cndmask_b32_e64 v65, v65, v72, s[2:3]
	v_cmp_lt_f32_e64 s[2:3], 0, v75
	s_nop 1
	v_cndmask_b32_e64 v65, v65, v73, s[2:3]
	v_mul_f32_e32 v72, 0x37800000, v65
	v_cndmask_b32_e32 v65, v65, v72, vcc
	v_cmp_class_f32_e32 vcc, v35, v51
	s_nop 1
	v_cndmask_b32_e32 v35, v65, v35, vcc
	v_div_scale_f32 v65, s[2:3], v35, v35, 1.0
	v_rcp_f32_e32 v73, v65
	v_div_scale_f32 v72, vcc, 1.0, v35, 1.0
	v_fma_f32 v74, -v65, v73, 1.0
	v_fmac_f32_e32 v73, v74, v73
	v_mul_f32_e32 v74, v72, v73
	v_fma_f32 v75, -v65, v74, v72
	v_fmac_f32_e32 v74, v75, v73
	v_fma_f32 v65, -v65, v74, v72
	v_div_fmas_f32 v65, v65, v73, v74
	v_div_fixup_f32 v72, v65, v35, 1.0
	v_pk_mul_f32 v[28:29], v[28:29], v[72:73] op_sel_hi:[1,0]
	v_pk_mul_f32 v[30:31], v[30:31], v[72:73] op_sel_hi:[1,0]
	v_pk_mul_f32 v[28:29], v[120:121], v[28:29]
	v_pk_mul_f32 v[30:31], v[122:123], v[30:31]
	global_store_dwordx4 v[70:71], v[28:31], off
	v_pk_mul_f32 v[26:27], v[26:27], v[72:73] op_sel_hi:[1,0]
	v_pk_mul_f32 v[24:25], v[24:25], v[72:73] op_sel_hi:[1,0]
	v_pk_mul_f32 v[22:23], v[22:23], v[72:73] op_sel_hi:[1,0]
	v_pk_mul_f32 v[20:21], v[20:21], v[72:73] op_sel_hi:[1,0]
	v_pk_mul_f32 v[18:19], v[18:19], v[72:73] op_sel_hi:[1,0]
	v_pk_mul_f32 v[16:17], v[16:17], v[72:73] op_sel_hi:[1,0]
	v_pk_mul_f32 v[14:15], v[14:15], v[72:73] op_sel_hi:[1,0]
	v_pk_mul_f32 v[12:13], v[12:13], v[72:73] op_sel_hi:[1,0]
	v_pk_mul_f32 v[10:11], v[10:11], v[72:73] op_sel_hi:[1,0]
	v_pk_mul_f32 v[8:9], v[8:9], v[72:73] op_sel_hi:[1,0]
	v_pk_mul_f32 v[6:7], v[6:7], v[72:73] op_sel_hi:[1,0]
	v_pk_mul_f32 v[4:5], v[4:5], v[72:73] op_sel_hi:[1,0]
	v_pk_mul_f32 v[2:3], v[2:3], v[72:73] op_sel_hi:[1,0]
	v_pk_mul_f32 v[0:1], v[0:1], v[72:73] op_sel_hi:[1,0]
	v_pk_mul_f32 v[24:25], v[124:125], v[24:25]
	v_pk_mul_f32 v[26:27], v[126:127], v[26:27]
	global_store_dwordx4 v[70:71], v[24:27], off offset:1024
	v_pk_mul_f32 v[20:21], v[128:129], v[20:21]
	v_pk_mul_f32 v[22:23], v[130:131], v[22:23]
	global_store_dwordx4 v[70:71], v[20:23], off offset:2048
	v_pk_mul_f32 v[16:17], v[132:133], v[16:17]
	v_pk_mul_f32 v[18:19], v[134:135], v[18:19]
	global_store_dwordx4 v[70:71], v[16:19], off offset:3072
	v_add_co_u32_e32 v20, vcc, s14, v70
	v_pk_mul_f32 v[12:13], v[136:137], v[12:13]
	v_addc_co_u32_e32 v21, vcc, 0, v71, vcc
	v_pk_mul_f32 v[14:15], v[138:139], v[14:15]
	global_store_dwordx4 v[20:21], v[12:15], off
	v_cmp_lt_i32_e32 vcc, s17, v34
	s_or_b64 s[4:5], vcc, s[4:5]
	v_pk_mul_f32 v[8:9], v[140:141], v[8:9]
	v_pk_mul_f32 v[10:11], v[142:143], v[10:11]
	global_store_dwordx4 v[20:21], v[8:11], off offset:1024
	v_pk_mul_f32 v[4:5], v[4:5], v[144:145]
	v_pk_mul_f32 v[6:7], v[6:7], v[146:147]
	global_store_dwordx4 v[20:21], v[4:7], off offset:2048
	v_pk_mul_f32 v[0:1], v[0:1], v[148:149]
	v_pk_mul_f32 v[2:3], v[2:3], v[150:151]
	global_store_dwordx4 v[20:21], v[0:3], off offset:3072
	s_nop 1
	v_mov_b32_e32 v66, v120
	v_mov_b32_e32 v67, v121
	v_mov_b32_e32 v68, v122
	v_mov_b32_e32 v69, v123
	v_mov_b32_e32 v28, v124
	v_mov_b32_e32 v29, v125
	v_mov_b32_e32 v30, v126
	v_mov_b32_e32 v31, v127
	v_mov_b32_e32 v24, v128
	v_mov_b32_e32 v25, v129
	v_mov_b32_e32 v26, v130
	v_mov_b32_e32 v27, v131
	v_mov_b32_e32 v22, v134
	v_mov_b32_e32 v23, v135
	v_mov_b32_e32 v16, v136
	v_mov_b32_e32 v17, v137
	v_mov_b32_e32 v18, v138
	v_mov_b32_e32 v19, v139
	v_mov_b32_e32 v12, v140
	v_mov_b32_e32 v13, v141
	v_mov_b32_e32 v14, v142
	v_mov_b32_e32 v15, v143
	v_mov_b32_e32 v10, v146
	v_mov_b32_e32 v11, v147
	v_mov_b32_e32 v8, v144
	v_mov_b32_e32 v9, v145
	v_mov_b32_e32 v4, v148
	v_mov_b32_e32 v5, v149
	v_mov_b32_e32 v6, v150
	v_mov_b32_e32 v7, v151
	s_andn2_b64 exec, exec, s[4:5]
	s_cbranch_execnz .LBB0_1463
	s_branch .LBB0_1460
